# seam barrier: per-workgroup flag poll interval s_sleep 16 -> 6 (wake-up latency vs poll traffic)
# baseline (speedup 1.0000x reference)
.Lseam_poll:
	s_sleep 6
	global_load_dword v0, v1, s[6:7] sc1
	s_waitcnt vmcnt(0)
	v_cmp_gt_u32_e32 vcc, s26, v0
	s_cbranch_vccnz .Lseam_poll
	s_branch .LBB0_109
